# v68 + attention: the first QK^T MFMA of each half-step issued right after the step barrier, ahead of its 3 / 6 lead-in VALU and LDS instructions (they run in its shadow)
# speedup vs baseline: 1.0105x; 1.0105x over previous
.LBB0_1604:
	s_waitcnt lgkmcnt(7)
	v_mfma_f32_32x32x16_bf16 v[112:127], v[204:207], v[172:175], 0
	v_add_u32_e32 v0, s22, v244
	ds_read_b64_tr_b16 v[208:209], v0 offset:24576
	ds_read_b64_tr_b16 v[210:211], v0 offset:25088
	v_add_f32_e32 v2, v87, v88
	v_cvt_pk_bf16_f32 v156, v96, v97
	v_cvt_pk_bf16_f32 v157, v98, v99
	ds_read_b64_tr_b16 v[204:205], v0 offset:28672
	ds_read_b64_tr_b16 v[206:207], v0 offset:29184
	v_add_f32_e32 v2, v89, v2
	v_cvt_pk_bf16_f32 v158, v100, v101
	v_cvt_pk_bf16_f32 v159, v102, v103
	s_waitcnt lgkmcnt(10)
	v_mfma_f32_32x32x16_bf16 v[128:143], v[200:203], v[172:175], 0
	ds_read_b64_tr_b16 v[10:11], v0 offset:25600
	ds_read_b64_tr_b16 v[12:13], v0 offset:26112
	s_waitcnt lgkmcnt(11)
	v_mfma_f32_32x32x16_bf16 v[112:127], v[196:199], v[168:171], v[112:127]
	v_add_f32_e32 v2, v90, v2
	v_cvt_pk_bf16_f32 v152, v104, v105
	v_cvt_pk_bf16_f32 v153, v106, v107
	ds_read_b64_tr_b16 v[6:7], v0 offset:29696
	ds_read_b64_tr_b16 v[8:9], v0 offset:30208
	v_add_f32_e32 v14, v91, v2
	v_cvt_pk_bf16_f32 v154, v108, v109
	v_cvt_pk_bf16_f32 v155, v110, v111
	s_waitcnt lgkmcnt(12)
	v_mfma_f32_32x32x16_bf16 v[128:143], v[192:195], v[168:171], v[128:143]
	ds_read_b64_tr_b16 v[2:3], v0 offset:26624
	ds_read_b64_tr_b16 v[4:5], v0 offset:27136
	s_waitcnt lgkmcnt(13)
	v_mfma_f32_32x32x16_bf16 v[112:127], v[188:191], v[164:167], v[112:127]
	v_add_f32_e32 v14, v92, v14
	v_cvt_pk_bf16_f32 v148, v80, v81
	v_cvt_pk_bf16_f32 v149, v82, v83
	ds_read_b64_tr_b16 v[196:197], v0 offset:30720
	ds_read_b64_tr_b16 v[198:199], v0 offset:31232
	v_add_f32_e32 v14, v93, v14
	v_cvt_pk_bf16_f32 v150, v84, v85
	v_cvt_pk_bf16_f32 v151, v86, v87
	s_waitcnt lgkmcnt(14)
	v_mfma_f32_32x32x16_bf16 v[128:143], v[184:187], v[164:167], v[128:143]
	ds_read_b64_tr_b16 v[192:193], v0 offset:27648
	ds_read_b64_tr_b16 v[194:195], v0 offset:28160
	s_waitcnt lgkmcnt(14)
	v_mfma_f32_32x32x16_bf16 v[112:127], v[180:183], v[160:163], v[112:127]
	v_add_f32_e32 v14, v94, v14
	v_cvt_pk_bf16_f32 v144, v88, v89
	v_cvt_pk_bf16_f32 v145, v90, v91
	ds_read_b64_tr_b16 v[188:189], v0 offset:31744
	ds_read_b64_tr_b16 v[190:191], v0 offset:32256
	v_add_f32_e32 v96, v95, v14
	v_cvt_pk_bf16_f32 v146, v92, v93
	v_cvt_pk_bf16_f32 v147, v94, v95
	v_mfma_f32_32x32x16_bf16 v[128:143], v[176:179], v[160:163], v[128:143]
	s_nop 2
	v_add_f32_e64 v80, v112, -v228
	v_add_f32_e64 v81, v113, -v228
	v_pk_add_f32 v[98:99], v[114:115], v[228:229] op_sel_hi:[1,0] neg_lo:[0,1] neg_hi:[0,1]
	v_pk_add_f32 v[100:101], v[116:117], v[228:229] op_sel_hi:[1,0] neg_lo:[0,1] neg_hi:[0,1]
	v_pk_add_f32 v[102:103], v[118:119], v[228:229] op_sel_hi:[1,0] neg_lo:[0,1] neg_hi:[0,1]
	v_pk_add_f32 v[104:105], v[120:121], v[228:229] op_sel_hi:[1,0] neg_lo:[0,1] neg_hi:[0,1]
	v_pk_add_f32 v[106:107], v[122:123], v[228:229] op_sel_hi:[1,0] neg_lo:[0,1] neg_hi:[0,1]
	v_pk_add_f32 v[108:109], v[124:125], v[228:229] op_sel_hi:[1,0] neg_lo:[0,1] neg_hi:[0,1]
	v_pk_add_f32 v[110:111], v[126:127], v[228:229] op_sel_hi:[1,0] neg_lo:[0,1] neg_hi:[0,1]
	v_max_f32_e32 v97, v80, v81
	s_add_u32 s30, s16, s10
	v_pk_add_f32 v[14:15], v[128:129], v[228:229] op_sel_hi:[1,0] neg_lo:[0,1] neg_hi:[0,1]
	v_max3_f32 v112, v98, v99, v100
	s_addc_u32 s31, s17, s11
	v_pk_add_f32 v[82:83], v[130:131], v[228:229] op_sel_hi:[1,0] neg_lo:[0,1] neg_hi:[0,1]
	v_max3_f32 v97, v97, v101, v102
	s_add_u32 s22, s30, 0x80000
	v_pk_add_f32 v[84:85], v[132:133], v[228:229] op_sel_hi:[1,0] neg_lo:[0,1] neg_hi:[0,1]
	v_max3_f32 v112, v112, v103, v104
	s_addc_u32 s23, s31, 0
	v_pk_add_f32 v[86:87], v[134:135], v[228:229] op_sel_hi:[1,0] neg_lo:[0,1] neg_hi:[0,1]
	v_max3_f32 v97, v97, v105, v106
	s_add_i32 s24, s29, s57
	v_pk_add_f32 v[88:89], v[136:137], v[228:229] op_sel_hi:[1,0] neg_lo:[0,1] neg_hi:[0,1]
	v_max3_f32 v112, v112, v107, v108
	s_add_u32 s62, s18, s10
	v_pk_add_f32 v[90:91], v[138:139], v[228:229] op_sel_hi:[1,0] neg_lo:[0,1] neg_hi:[0,1]
	v_max3_f32 v97, v97, v109, v110
	s_addc_u32 s63, s19, s11
	v_pk_add_f32 v[92:93], v[140:141], v[228:229] op_sel_hi:[1,0] neg_lo:[0,1] neg_hi:[0,1]
	v_max3_f32 v112, v112, v111, v14
	v_pk_add_f32 v[94:95], v[142:143], v[228:229] op_sel_hi:[1,0] neg_lo:[0,1] neg_hi:[0,1]
	v_max3_f32 v97, v97, v15, v82
	v_max3_f32 v112, v112, v83, v84
	v_max3_f32 v97, v97, v85, v86
	v_max3_f32 v112, v112, v87, v88
	v_max3_f32 v97, v97, v89, v90
	v_max3_f32 v112, v112, v91, v92
	v_max3_f32 v97, v97, v94, v95
	s_mov_b32 s25, m0
	s_mov_b32 m0, s24
	s_nop 0
	global_load_lds_dwordx4 v241, s[22:23]
	s_mov_b32 m0, s25
	s_add_u32 s22, s62, 0x40000
	v_add_f32_e32 v116, v224, v96
	v_max3_f32 v96, v97, v93, v112
	s_addc_u32 s23, s63, 0
	s_add_i32 s24, s28, s58
	v_mov_b32_e32 v97, v96
	s_add_u32 s64, s20, s10
	s_nop 0
	v_permlane32_swap_b32_e32 v96, v97
	s_addc_u32 s65, s21, s11
	s_mov_b32 s25, m0
	s_mov_b32 m0, s24
	s_nop 0
	global_load_lds_dwordx4 v242, s[22:23]
	s_mov_b32 m0, s25
	s_add_u32 s22, s64, 0x40000
	v_max_f32_e32 v96, v96, v97
	s_addc_u32 s23, s65, 0
	s_add_i32 s24, s28, s59
	s_mov_b32 s25, m0
	s_mov_b32 m0, s24
	s_nop 0
	global_load_lds_dwordx4 v242, s[22:23]
	s_mov_b32 m0, s25
	v_cmp_lt_f32_e32 vcc, s35, v96
	s_cmp_lg_u64 vcc, 0
	s_cselect_b64 s[22:23], -1, 0
	s_cbranch_vccnz .LBB0_1612

.LBB0_1607:
	s_add_i32 s22, s28, 0x2000
	s_cmpk_lg_i32 s28, 0x4000
	s_cselect_b32 s61, s22, 0
	v_add_f32_e32 v15, v116, v14
	v_mfma_f32_32x32x16_bf16 v[112:127], v[112:115], v[172:175], 0
	v_add_u32_e32 v14, s29, v244
	ds_read_b64_tr_b16 v[196:197], v14 offset:24576
	ds_read_b64_tr_b16 v[198:199], v14 offset:25088
	v_add_f32_e32 v132, v87, v88
	v_cvt_pk_bf16_f32 v156, v96, v97
	v_cvt_pk_bf16_f32 v157, v98, v99
	ds_read_b64_tr_b16 v[192:193], v14 offset:28672
	ds_read_b64_tr_b16 v[194:195], v14 offset:29184
	v_add_f32_e32 v96, v89, v132
	v_cvt_pk_bf16_f32 v158, v100, v101
	v_cvt_pk_bf16_f32 v159, v102, v103
	v_mfma_f32_32x32x16_bf16 v[128:143], v[128:131], v[172:175], 0
	ds_read_b64_tr_b16 v[188:189], v14 offset:25600
	ds_read_b64_tr_b16 v[190:191], v14 offset:26112
	v_add_f32_e32 v96, v90, v96
	v_cvt_pk_bf16_f32 v152, v104, v105
	v_cvt_pk_bf16_f32 v153, v106, v107
	v_mfma_f32_32x32x16_bf16 v[112:127], v[184:187], v[168:171], v[112:127]
	ds_read_b64_tr_b16 v[184:185], v14 offset:29696
	ds_read_b64_tr_b16 v[186:187], v14 offset:30208
	v_add_f32_e32 v96, v91, v96
	v_cvt_pk_bf16_f32 v154, v108, v109
	v_cvt_pk_bf16_f32 v155, v110, v111
	v_mfma_f32_32x32x16_bf16 v[128:143], v[176:179], v[168:171], v[128:143]
	ds_read_b64_tr_b16 v[176:177], v14 offset:26624
	ds_read_b64_tr_b16 v[178:179], v14 offset:27136
	v_add_f32_e32 v96, v92, v96
	v_cvt_pk_bf16_f32 v148, v80, v81
	v_cvt_pk_bf16_f32 v149, v82, v83
	v_mfma_f32_32x32x16_bf16 v[112:127], v[180:183], v[164:167], v[112:127]
	ds_read_b64_tr_b16 v[212:213], v14 offset:30720
	ds_read_b64_tr_b16 v[214:215], v14 offset:31232
	v_add_f32_e32 v80, v93, v96
	v_cvt_pk_bf16_f32 v150, v84, v85
	v_cvt_pk_bf16_f32 v151, v86, v87
	v_mfma_f32_32x32x16_bf16 v[128:143], v[6:9], v[164:167], v[128:143]
	ds_read_b64_tr_b16 v[208:209], v14 offset:27648
	ds_read_b64_tr_b16 v[210:211], v14 offset:28160
	v_add_f32_e32 v80, v94, v80
	v_cvt_pk_bf16_f32 v144, v88, v89
	v_cvt_pk_bf16_f32 v145, v90, v91
	v_mfma_f32_32x32x16_bf16 v[112:127], v[10:13], v[160:163], v[112:127]
	ds_read_b64_tr_b16 v[6:7], v14 offset:31744
	ds_read_b64_tr_b16 v[8:9], v14 offset:32256
	v_add_f32_e32 v10, v95, v80
	v_cvt_pk_bf16_f32 v146, v92, v93
	v_cvt_pk_bf16_f32 v147, v94, v95
	v_mfma_f32_32x32x16_bf16 v[128:143], v[2:5], v[160:163], v[128:143]
	s_nop 5
	v_add_f32_e64 v4, v112, -v228
	v_add_f32_e64 v5, v113, -v228
	v_pk_add_f32 v[98:99], v[114:115], v[228:229] op_sel_hi:[1,0] neg_lo:[0,1] neg_hi:[0,1]
	v_pk_add_f32 v[100:101], v[116:117], v[228:229] op_sel_hi:[1,0] neg_lo:[0,1] neg_hi:[0,1]
	v_pk_add_f32 v[102:103], v[118:119], v[228:229] op_sel_hi:[1,0] neg_lo:[0,1] neg_hi:[0,1]
	v_pk_add_f32 v[104:105], v[120:121], v[228:229] op_sel_hi:[1,0] neg_lo:[0,1] neg_hi:[0,1]
	v_pk_add_f32 v[106:107], v[122:123], v[228:229] op_sel_hi:[1,0] neg_lo:[0,1] neg_hi:[0,1]
	v_pk_add_f32 v[108:109], v[124:125], v[228:229] op_sel_hi:[1,0] neg_lo:[0,1] neg_hi:[0,1]
	v_pk_add_f32 v[110:111], v[126:127], v[228:229] op_sel_hi:[1,0] neg_lo:[0,1] neg_hi:[0,1]
	v_max_f32_e32 v11, v4, v5
	s_add_u32 s22, s30, 0xa0000
	v_pk_add_f32 v[2:3], v[128:129], v[228:229] op_sel_hi:[1,0] neg_lo:[0,1] neg_hi:[0,1]
	v_max3_f32 v12, v98, v99, v100
	v_pk_add_f32 v[82:83], v[130:131], v[228:229] op_sel_hi:[1,0] neg_lo:[0,1] neg_hi:[0,1]
	v_max3_f32 v11, v11, v101, v102
	v_pk_add_f32 v[84:85], v[132:133], v[228:229] op_sel_hi:[1,0] neg_lo:[0,1] neg_hi:[0,1]
	v_max3_f32 v12, v12, v103, v104
	v_pk_add_f32 v[86:87], v[134:135], v[228:229] op_sel_hi:[1,0] neg_lo:[0,1] neg_hi:[0,1]
	v_max3_f32 v11, v11, v105, v106
	v_pk_add_f32 v[88:89], v[136:137], v[228:229] op_sel_hi:[1,0] neg_lo:[0,1] neg_hi:[0,1]
	v_max3_f32 v12, v12, v107, v108
	v_pk_add_f32 v[90:91], v[138:139], v[228:229] op_sel_hi:[1,0] neg_lo:[0,1] neg_hi:[0,1]
	v_max3_f32 v11, v11, v109, v110
	v_pk_add_f32 v[92:93], v[140:141], v[228:229] op_sel_hi:[1,0] neg_lo:[0,1] neg_hi:[0,1]
	v_max3_f32 v12, v12, v111, v2
	v_pk_add_f32 v[94:95], v[142:143], v[228:229] op_sel_hi:[1,0] neg_lo:[0,1] neg_hi:[0,1]
	v_max3_f32 v11, v11, v3, v82
	v_max3_f32 v12, v12, v83, v84
	v_max3_f32 v11, v11, v85, v86
	v_max3_f32 v12, v12, v87, v88
	v_max3_f32 v11, v11, v89, v90
	v_max3_f32 v12, v12, v91, v92
	v_max3_f32 v11, v11, v94, v95
	v_max3_f32 v11, v11, v93, v12
	s_addc_u32 s23, s31, 0
	s_add_i32 s24, s28, s57
	v_mov_b32_e32 v12, v11
	s_mov_b32 s25, m0
	s_mov_b32 m0, s24
	s_nop 0
	global_load_lds_dwordx4 v241, s[22:23]
	s_mov_b32 m0, s25
	s_add_u32 s22, s62, 0x60000
	s_nop 0
	v_permlane32_swap_b32_e32 v11, v12
	s_addc_u32 s23, s63, 0
	s_add_i32 s24, s61, s58
	s_mov_b32 s25, m0
	s_mov_b32 m0, s24
	s_nop 0
	global_load_lds_dwordx4 v242, s[22:23]
	s_mov_b32 m0, s25
	s_add_u32 s22, s64, 0x60000
	v_max_f32_e32 v11, v11, v12
	s_addc_u32 s23, s65, 0
	s_add_i32 s24, s61, s59
	s_mov_b32 s25, m0
	s_mov_b32 m0, s24
	s_nop 0
	global_load_lds_dwordx4 v242, s[22:23]
	s_mov_b32 m0, s25
	v_cmp_lt_f32_e32 vcc, s35, v11
	s_cmp_lg_u64 vcc, 0
	v_add_f32_e32 v10, v15, v10
	s_cselect_b64 s[22:23], -1, 0
	s_cbranch_vccnz .LBB0_1615
